# sparse work split: K/V block load charged 0.75 tile instead of 0.5 (v75 otherwise)
# speedup vs baseline: 1.0078x; 1.0078x over previous
.LBB0_789:
	s_or_b64 exec, exec, s[4:5]
	v_and_b32_e32 v1, 63, v0
	s_cmp_lt_u32 s33, 64
	v_and_b32_e32 v7, 64, v6
	v_cmp_gt_u32_e32 vcc, 32, v1
	s_waitcnt lgkmcnt(0)
	s_barrier
	s_cbranch_scc0 .LBB0_793
	v_lshlrev_b32_e32 v20, 6, v1
	v_add_u32_e32 v2, 0, v20
	v_add_u32_e32 v16, 0x20400, v2
	ds_read_b128 v[2:5], v16
	s_movk_i32 s6, 0xff
	ds_read_b128 v[8:11], v16 offset:16
	ds_read_b128 v[12:15], v16 offset:32
	ds_read_b128 v[16:19], v16 offset:48
	v_add_u32_e32 v38, -2, v6
	s_add_i32 s16, 0, 0x21400
	s_waitcnt lgkmcnt(3)
	v_add_u32_e32 v2, 0xff, v2
	v_add_u32_e32 v3, 0xff, v3
	v_lshrrev_b32_e32 v24, 8, v2
	v_lshl_add_u32 v24, v24, 3, 6
	v_lshrrev_b32_e32 v23, 8, v3
	v_lshl_add_u32 v23, v23, 3, 6
	v_cmp_lt_u32_e64 s[4:5], s6, v2
	v_lshrrev_b32_e32 v21, 8, v2
	v_cndmask_b32_e64 v24, 0, v24, s[4:5]
	v_cmp_lt_u32_e64 s[4:5], s6, v3
	v_lshrrev_b32_e32 v22, 8, v3
	s_waitcnt lgkmcnt(2)
	v_add_u32_e32 v8, 0xff, v8
	v_cndmask_b32_e64 v2, 0, v23, s[4:5]
	v_add_u32_e32 v23, v2, v24
	v_add_u32_e32 v2, 0xff, v4
	v_lshrrev_b32_e32 v4, 8, v2
	v_lshl_add_u32 v4, v4, 3, 6
	v_cmp_lt_u32_e64 s[4:5], s6, v2
	v_lshrrev_b32_e32 v3, 8, v2
	v_lshrrev_b32_e32 v26, 8, v8
	v_lshl_add_u32 v26, v26, 3, 6
	v_cndmask_b32_e64 v2, 0, v4, s[4:5]
	v_add_u32_e32 v4, 0xff, v5
	v_lshrrev_b32_e32 v25, 8, v4
	v_lshl_add_u32 v25, v25, 3, 6
	v_cmp_lt_u32_e64 s[4:5], s6, v4
	v_add_u32_e32 v9, 0xff, v9
	v_lshrrev_b32_e32 v5, 8, v4
	v_cndmask_b32_e64 v4, 0, v25, s[4:5]
	v_cmp_lt_u32_e64 s[4:5], s6, v8
	v_lshrrev_b32_e32 v27, 8, v9
	v_lshl_add_u32 v27, v27, 3, 6
	v_add_u32_e32 v10, 0xff, v10
	v_add_u32_e32 v22, v22, v21
	v_lshrrev_b32_e32 v25, 8, v8
	v_cndmask_b32_e64 v8, 0, v26, s[4:5]
	v_cmp_lt_u32_e64 s[4:5], s6, v9
	v_lshrrev_b32_e32 v28, 8, v10
	v_lshl_add_u32 v28, v28, 3, 6
	v_add_u32_e32 v11, 0xff, v11
	v_lshrrev_b32_e32 v26, 8, v9
	v_cndmask_b32_e64 v9, 0, v27, s[4:5]
	v_cmp_lt_u32_e64 s[4:5], s6, v10
	v_lshrrev_b32_e32 v29, 8, v11
	v_lshl_add_u32 v29, v29, 3, 6
	s_waitcnt lgkmcnt(1)
	v_add_u32_e32 v12, 0xff, v12
	v_add_u32_e32 v3, v3, v22
	v_lshrrev_b32_e32 v27, 8, v10
	v_cndmask_b32_e64 v10, 0, v28, s[4:5]
	v_cmp_lt_u32_e64 s[4:5], s6, v11
	v_lshrrev_b32_e32 v30, 8, v12
	v_lshl_add_u32 v30, v30, 3, 6
	v_add_u32_e32 v13, 0xff, v13
	v_add_u32_e32 v5, v5, v3
	v_lshrrev_b32_e32 v28, 8, v11
	v_cndmask_b32_e64 v11, 0, v29, s[4:5]
	v_cmp_lt_u32_e64 s[4:5], s6, v12
	v_lshrrev_b32_e32 v31, 8, v13
	v_lshl_add_u32 v31, v31, 3, 6
	v_add_u32_e32 v14, 0xff, v14
	v_add_u32_e32 v25, v25, v5
	v_lshrrev_b32_e32 v29, 8, v12
	v_cndmask_b32_e64 v12, 0, v30, s[4:5]
	v_cmp_lt_u32_e64 s[4:5], s6, v13
	v_lshrrev_b32_e32 v32, 8, v14
	v_lshl_add_u32 v32, v32, 3, 6
	v_add_u32_e32 v15, 0xff, v15
	v_add_u32_e32 v26, v26, v25
	v_lshrrev_b32_e32 v30, 8, v13
	v_cndmask_b32_e64 v13, 0, v31, s[4:5]
	v_cmp_lt_u32_e64 s[4:5], s6, v14
	v_lshrrev_b32_e32 v33, 8, v15
	v_lshl_add_u32 v33, v33, 3, 6
	s_waitcnt lgkmcnt(0)
	v_add_u32_e32 v16, 0xff, v16
	v_add_u32_e32 v27, v27, v26
	v_lshrrev_b32_e32 v31, 8, v14
	v_cndmask_b32_e64 v14, 0, v32, s[4:5]
	v_cmp_lt_u32_e64 s[4:5], s6, v15
	v_lshrrev_b32_e32 v34, 8, v16
	v_lshl_add_u32 v34, v34, 3, 6
	v_add_u32_e32 v17, 0xff, v17
	v_add_u32_e32 v28, v28, v27
	v_lshrrev_b32_e32 v32, 8, v15
	v_cndmask_b32_e64 v15, 0, v33, s[4:5]
	v_cmp_lt_u32_e64 s[4:5], s6, v16
	v_lshrrev_b32_e32 v35, 8, v17
	v_lshl_add_u32 v35, v35, 3, 6
	v_add_u32_e32 v18, 0xff, v18
	v_add_u32_e32 v29, v29, v28
	v_lshrrev_b32_e32 v33, 8, v16
	v_cndmask_b32_e64 v16, 0, v34, s[4:5]
	v_cmp_lt_u32_e64 s[4:5], s6, v17
	v_lshrrev_b32_e32 v36, 8, v18
	v_lshl_add_u32 v36, v36, 3, 6
	v_add_u32_e32 v19, 0xff, v19
	v_add_u32_e32 v30, v30, v29
	v_lshrrev_b32_e32 v34, 8, v17
	v_cndmask_b32_e64 v17, 0, v35, s[4:5]
	v_cmp_lt_u32_e64 s[4:5], s6, v18
	v_lshrrev_b32_e32 v37, 8, v19
	v_lshl_add_u32 v37, v37, 3, 6
	v_add_u32_e32 v31, v31, v30
	v_lshrrev_b32_e32 v35, 8, v18
	v_cndmask_b32_e64 v18, 0, v36, s[4:5]
	v_cmp_lt_u32_e64 s[4:5], s6, v19
	v_add_u32_e32 v32, v32, v31
	v_lshrrev_b32_e32 v36, 8, v19
	v_cndmask_b32_e64 v19, 0, v37, s[4:5]
	v_add_u32_e32 v37, -1, v6
	v_add_u32_e32 v33, v33, v32
	v_cmp_lt_i32_e64 s[4:5], v37, v7
	v_add_u32_e32 v47, v2, v23
	v_add_u32_e32 v34, v34, v33
	v_cndmask_b32_e64 v37, v37, v6, s[4:5]
	s_add_i32 s17, 0, 0x22800
	v_add_u32_e32 v4, v4, v47
	v_or_b32_e32 v2, 20, v20
	v_add_u32_e32 v35, v35, v34
	v_lshlrev_b32_e32 v37, 2, v37
	v_cmp_lt_i32_e64 s[4:5], v38, v7
	v_add_u32_e32 v39, -4, v6
	v_add_u32_e32 v48, s16, v2
	v_add_u32_e32 v49, s17, v2
	v_add_u32_e32 v50, v8, v4
	v_or_b32_e32 v2, 28, v20
	v_add_u32_e32 v8, v36, v35
	v_cndmask_b32_e64 v38, v38, v6, s[4:5]
	v_cmp_lt_i32_e64 s[4:5], v39, v7
	v_add_u32_e32 v40, -8, v6
	v_add_u32_e32 v52, s16, v2
	v_add_u32_e32 v53, s17, v2
	ds_bpermute_b32 v2, v37, v8
	v_cndmask_b32_e64 v39, v39, v6, s[4:5]
	v_cmp_lt_i32_e64 s[4:5], v40, v7
	v_add_u32_e32 v41, -16, v6
	v_subrev_u32_e32 v42, 32, v6
	v_cndmask_b32_e64 v40, v40, v6, s[4:5]
	v_cmp_lt_i32_e64 s[4:5], v41, v7
	v_lshlrev_b32_e32 v38, 2, v38
	v_add_u32_e32 v51, v9, v50
	v_cndmask_b32_e64 v41, v41, v6, s[4:5]
	v_cmp_lt_i32_e64 s[4:5], v42, v7
	v_add_u32_e32 v36, v10, v51
	v_or_b32_e32 v9, 36, v20
	v_cndmask_b32_e64 v42, v42, v6, s[4:5]
	v_cmp_eq_u32_e64 s[4:5], 0, v1
	v_cmp_gt_u32_e64 s[6:7], 2, v1
	v_add_u32_e32 v54, v11, v36
	s_waitcnt lgkmcnt(0)
	v_cndmask_b32_e64 v2, v2, 0, s[4:5]
	v_add_u32_e32 v2, v8, v2
	ds_bpermute_b32 v10, v38, v2
	v_add_u32_e32 v11, s16, v9
	v_add_u32_e32 v55, s17, v9
	v_lshlrev_b32_e32 v39, 2, v39
	v_cmp_gt_u32_e64 s[8:9], 4, v1
	s_waitcnt lgkmcnt(0)
	v_cndmask_b32_e64 v9, v10, 0, s[6:7]
	v_add_u32_e32 v2, v2, v9
	ds_bpermute_b32 v9, v39, v2
	v_lshlrev_b32_e32 v40, 2, v40
	v_cmp_gt_u32_e64 s[10:11], 8, v1
	v_lshlrev_b32_e32 v41, 2, v41
	v_add_u32_e32 v56, v12, v54
	s_waitcnt lgkmcnt(0)
	v_cndmask_b32_e64 v9, v9, 0, s[8:9]
	v_add_u32_e32 v2, v9, v2
	ds_bpermute_b32 v9, v40, v2
	v_add_u32_e32 v13, v13, v56
	v_add_u32_e32 v14, v14, v13
	v_add_u32_e32 v15, v15, v14
	v_cmp_gt_u32_e64 s[12:13], 16, v1
	s_waitcnt lgkmcnt(0)
	v_cndmask_b32_e64 v9, v9, 0, s[10:11]
	v_add_u32_e32 v2, v9, v2
	ds_bpermute_b32 v9, v41, v2
	v_add_u32_e32 v16, v16, v15
	v_lshlrev_b32_e32 v42, 2, v42
	v_add_u32_e32 v17, v17, v16
	v_add_u32_e32 v18, v18, v17
	s_waitcnt lgkmcnt(0)
	v_cndmask_b32_e64 v9, v9, 0, s[12:13]
	v_add_u32_e32 v2, v9, v2
	ds_bpermute_b32 v9, v42, v2
	v_add_u32_e32 v19, v19, v18
	ds_bpermute_b32 v37, v37, v19
	v_or_b32_e32 v10, 44, v20
	v_add_u32_e32 v12, s16, v10
	s_waitcnt lgkmcnt(1)
	v_cndmask_b32_e64 v9, v9, 0, vcc
	v_add_u32_e32 v2, v9, v2
	v_add_u32_e32 v57, s17, v10
	v_or_b32_e32 v10, 52, v20
	v_sub_u32_e32 v8, v2, v8
	s_waitcnt lgkmcnt(0)
	v_cndmask_b32_e64 v9, v37, 0, s[4:5]
	v_add_u32_e32 v58, s16, v10
	v_add_u32_e32 v59, s17, v10
	v_add_u32_e32 v10, v8, v22
	v_add_u32_e32 v22, v19, v9
	ds_bpermute_b32 v37, v38, v22
	v_add_u32_e32 v43, s16, v20
	v_add_u32_e32 v9, v8, v21
	ds_write_b96 v43, v[8:10]
	v_or_b32_e32 v45, 12, v20
	s_waitcnt lgkmcnt(1)
	v_cndmask_b32_e64 v9, v37, 0, s[6:7]
	v_add_u32_e32 v9, v22, v9
	ds_bpermute_b32 v10, v39, v9
	v_add_u32_e32 v46, s16, v45
	v_add_u32_e32 v5, v8, v5
	v_add_u32_e32 v3, v8, v3
	ds_write2_b32 v46, v3, v5 offset1:1
	v_add_u32_e32 v3, v8, v26
	v_add_u32_e32 v5, v8, v25
	ds_write2_b32 v48, v5, v3 offset1:1
	s_waitcnt lgkmcnt(2)
	v_cndmask_b32_e64 v3, v10, 0, s[8:9]
	v_add_u32_e32 v3, v9, v3
	ds_bpermute_b32 v5, v40, v3
	v_add_u32_e32 v9, v8, v28
	v_add_u32_e32 v10, v8, v27
	ds_write2_b32 v52, v10, v9 offset1:1
	v_add_u32_e32 v9, v8, v30
	s_waitcnt lgkmcnt(1)
	v_cndmask_b32_e64 v5, v5, 0, s[10:11]
	v_add_u32_e32 v3, v3, v5
	ds_bpermute_b32 v5, v41, v3
	v_add_u32_e32 v10, v8, v29
	ds_write2_b32 v11, v10, v9 offset1:1
	v_add_u32_e32 v9, v8, v32
	v_add_u32_e32 v10, v8, v31
	s_waitcnt lgkmcnt(1)
	v_cndmask_b32_e64 v5, v5, 0, s[12:13]
	v_add_u32_e32 v3, v5, v3
	ds_bpermute_b32 v5, v42, v3
	ds_write2_b32 v12, v10, v9 offset1:1
	v_add_u32_e32 v9, v8, v34
	v_add_u32_e32 v10, v8, v33
	ds_write2_b32 v58, v10, v9 offset1:1
	s_waitcnt lgkmcnt(2)
	v_cndmask_b32_e64 v5, v5, 0, vcc
	v_add_u32_e32 v3, v5, v3
	v_sub_u32_e32 v10, v3, v19
	v_add_u32_e32 v45, s17, v45
	v_add_u32_e32 v4, v10, v4
	v_add_u32_e32 v5, v10, v47
	ds_write2_b32 v45, v5, v4 offset1:1
	v_add_u32_e32 v4, v10, v51
	v_add_u32_e32 v5, v10, v50
	ds_write2_b32 v49, v5, v4 offset1:1
	v_add_u32_e32 v4, v10, v54
	v_add_u32_e32 v5, v10, v36
	ds_write2_b32 v53, v5, v4 offset1:1
	v_add_u32_e32 v4, v10, v13
	v_add_u32_e32 v5, v10, v56
	ds_write2_b32 v55, v5, v4 offset1:1
	v_add_u32_e32 v4, v10, v15
	v_add_u32_e32 v5, v10, v14
	ds_write2_b32 v57, v5, v4 offset1:1
	v_add_u32_e32 v4, v10, v17
	v_add_u32_e32 v5, v10, v16
	ds_write2_b32 v59, v5, v4 offset1:1
	v_or_b32_e32 v5, 60, v20
	v_add_u32_e32 v4, v8, v35
	v_add_u32_e32 v8, s16, v5
	v_add_u32_e32 v44, s17, v20
	v_add_u32_e32 v12, v10, v23
	v_add_u32_e32 v11, v10, v24
	ds_write_b32 v8, v4
	v_add_u32_e32 v4, v10, v18
	v_add_u32_e32 v5, s17, v5
	v_cmp_eq_u32_e32 vcc, 63, v1
	ds_write_b96 v44, v[10:12]
	ds_write_b32 v5, v4
	s_and_saveexec_b64 s[4:5], vcc
	s_cbranch_execz .LBB0_792
	s_add_i32 s6, 0, 0x22400
	v_mov_b32_e32 v4, s6
	s_add_i32 s6, 0, 0x23800
	ds_write_b32 v4, v2
	v_mov_b32_e32 v2, s6
	ds_write_b32 v2, v3

.LBB0_798:
	s_add_i32 s7, s5, s4
	s_ashr_i32 s7, s7, 1
	s_lshl_b32 s10, s7, 2
	s_add_i32 s10, s10, 0
	s_add_i32 s10, s10, 0x22800
	v_mov_b32_e32 v4, s10
	ds_read_b32 v4, v4
	s_waitcnt lgkmcnt(0)
	v_readfirstlane_b32 s10, v4
	s_cmp_gt_u32 s10, s6
	s_cselect_b32 s5, s7, s5
	s_cselect_b32 s4, s4, s7
	s_sub_i32 s7, s5, s4
	s_cmp_gt_i32 s7, 1
	s_cbranch_scc1 .LBB0_798
	s_lshl_b32 s4, s4, 2
	s_add_i32 s4, s4, 0
	s_add_i32 s5, s4, 0x21400
	s_add_i32 s4, s4, 0x22800
	v_mov_b32_e32 v4, s5
	v_mov_b32_e32 v8, s4
	ds_read2_b32 v[4:5], v4 offset1:1
	ds_read_b32 v8, v8
	s_waitcnt lgkmcnt(1)
	v_readfirstlane_b32 s4, v4
	s_waitcnt lgkmcnt(0)
	v_readfirstlane_b32 s10, v8
	v_readfirstlane_b32 s5, v5
	s_add_i32 s11, s10, 6
	s_sub_i32 s10, s6, s10
	s_sub_i32 s7, s5, s4
	s_add_i32 s10, s10, 1
	s_lshr_b32 s10, s10, 3
	s_cmp_lt_u32 s11, s6
	s_cselect_b32 s6, s10, 0
	s_add_i32 s4, s6, s4
	s_cmp_lt_u32 s6, s7
	s_cselect_b32 s66, s4, s5

.LBB0_805:
	s_add_i32 s7, s5, s4
	s_ashr_i32 s7, s7, 1
	s_lshl_b32 s8, s7, 2
	s_add_i32 s8, s8, 0
	s_add_i32 s8, s8, 0x22800
	v_mov_b32_e32 v2, s8
	ds_read_b32 v2, v2
	s_waitcnt lgkmcnt(0)
	v_readfirstlane_b32 s8, v2
	s_cmp_gt_u32 s8, s6
	s_cselect_b32 s5, s7, s5
	s_cselect_b32 s4, s4, s7
	s_sub_i32 s7, s5, s4
	s_cmp_gt_i32 s7, 1
	s_cbranch_scc1 .LBB0_805
	s_lshl_b32 s4, s4, 2
	s_add_i32 s4, s4, 0
	s_add_i32 s5, s4, 0x21400
	s_add_i32 s4, s4, 0x22800
	v_mov_b32_e32 v2, s5
	v_mov_b32_e32 v4, s4
	ds_read2_b32 v[2:3], v2 offset1:1
	ds_read_b32 v4, v4
	s_waitcnt lgkmcnt(1)
	v_sub_u32_e32 v5, v3, v2
	s_waitcnt lgkmcnt(0)
	v_add_u32_e32 v8, 6, v4
	v_sub_u32_e32 v4, s6, v4
	v_add_u32_e32 v4, 1, v4
	v_lshrrev_b32_e32 v4, 3, v4
	v_cmp_gt_u32_e32 vcc, s6, v8
	s_nop 1
	v_cndmask_b32_e32 v4, 0, v4, vcc
	v_add_u32_e32 v2, v4, v2
	v_cmp_lt_u32_e32 vcc, v4, v5
	s_nop 1
	v_cndmask_b32_e32 v186, v3, v2, vcc
